# layer-0 part-1 weight conversion also deferred from the prologue to the P1 exit idle slot
# speedup vs baseline: 1.0161x; 1.0048x over previous
.LBB0_20:
	v_writelane_b32 v253, s68, 40
	s_lshl_b32 s0, s80, 9
	v_add_u32_e32 v10, s0, v8
	v_writelane_b32 v253, s69, 41
	v_writelane_b32 v253, s70, 42
	v_writelane_b32 v253, s71, 43
	v_writelane_b32 v253, s72, 44
	v_writelane_b32 v253, s73, 45
	v_writelane_b32 v253, s74, 46
	v_writelane_b32 v253, s75, 47
	v_writelane_b32 v253, s0, 48
	s_lshl_b32 s92, s96, 9
	s_mov_b64 s[2:3], exec
	v_readlane_b32 s8, v253, 20
	v_readlane_b32 s9, v253, 21
	v_readlane_b32 s10, v253, 30
	v_readlane_b32 s11, v253, 31
	v_readlane_b32 s12, v253, 28
	v_readlane_b32 s13, v253, 29
	v_readlane_b32 s14, v253, 34
	v_readlane_b32 s15, v253, 35
	v_readlane_b32 s16, v253, 32
	v_readlane_b32 s17, v253, 33
	v_readlane_b32 s18, v253, 36
	v_readlane_b32 s19, v253, 37
	v_readlane_b32 s20, v253, 38
	v_readlane_b32 s21, v253, 39
	v_mov_b32_e32 v11, 0
	v_mov_b32_e32 v192, v10
	v_cmp_gt_u32_e32 vcc, 0x6d000, v192
	s_mov_b64 s[36:37], vcc
	v_lshrrev_b32_e32 v193, 6, v192
	s_mov_b32 s1, 0x12c9fb5
	v_mul_hi_u32 v194, v193, s1
	v_mul_u32_u24_e32 v193, 0xda, v194
	v_lshrrev_b32_e32 v232, 6, v192
	v_sub_u32_e32 v193, v232, v193
	v_bfe_u32 v232, v192, 4, 2
	v_lshl_add_u32 v232, v194, 2, v232
	v_and_b32_e32 v194, 15, v192
	v_lshl_add_u32 v194, v193, 4, v194
	v_mov_b32_e32 v193, v232
	v_mul_u32_u24_e32 v195, 0x37400, v193
	v_lshl_add_u32 v195, v194, 2, v195
	v_lshlrev_b32_e32 v196, 11, v194
	v_lshl_add_u32 v196, v193, 4, v196
	v_add_u32_e32 v196, 0x400000, v196
	s_mov_b64 exec, s[36:37]
	global_load_dword v104, v195, s[8:9]
	v_add_u32_e32 v195, 0x6e80, v195
	global_load_dword v105, v195, s[8:9]
	v_add_u32_e32 v195, 0x6e80, v195
	global_load_dword v106, v195, s[8:9]
	v_add_u32_e32 v195, 0x6e80, v195
	global_load_dword v107, v195, s[8:9]
	v_add_u32_e32 v195, 0x6e80, v195
	global_load_dword v108, v195, s[8:9]
	v_add_u32_e32 v195, 0x6e80, v195
	global_load_dword v109, v195, s[8:9]
	v_add_u32_e32 v195, 0x6e80, v195
	global_load_dword v110, v195, s[8:9]
	v_add_u32_e32 v195, 0x6e80, v195
	global_load_dword v111, v195, s[8:9]
	s_mov_b64 exec, s[2:3]
	s_mul_i32 s0, s92, 1
	v_add_u32_e32 v200, s0, v10
	v_cmp_gt_u32_e32 vcc, 0x6d000, v200
	s_mov_b64 s[38:39], vcc
	v_lshrrev_b32_e32 v201, 6, v200
	s_mov_b32 s1, 0x12c9fb5
	v_mul_hi_u32 v202, v201, s1
	v_mul_u32_u24_e32 v201, 0xda, v202
	v_lshrrev_b32_e32 v232, 6, v200
	v_sub_u32_e32 v201, v232, v201
	v_bfe_u32 v232, v200, 4, 2
	v_lshl_add_u32 v232, v202, 2, v232
	v_and_b32_e32 v202, 15, v200
	v_lshl_add_u32 v202, v201, 4, v202
	v_mov_b32_e32 v201, v232
	v_mul_u32_u24_e32 v203, 0x37400, v201
	v_lshl_add_u32 v203, v202, 2, v203
	v_lshlrev_b32_e32 v204, 11, v202
	v_lshl_add_u32 v204, v201, 4, v204
	v_add_u32_e32 v204, 0x400000, v204
	s_mov_b64 exec, s[38:39]
	global_load_dword v120, v203, s[8:9]
	v_add_u32_e32 v203, 0x6e80, v203
	global_load_dword v121, v203, s[8:9]
	v_add_u32_e32 v203, 0x6e80, v203
	global_load_dword v122, v203, s[8:9]
	v_add_u32_e32 v203, 0x6e80, v203
	global_load_dword v123, v203, s[8:9]
	v_add_u32_e32 v203, 0x6e80, v203
	global_load_dword v124, v203, s[8:9]
	v_add_u32_e32 v203, 0x6e80, v203
	global_load_dword v125, v203, s[8:9]
	v_add_u32_e32 v203, 0x6e80, v203
	global_load_dword v126, v203, s[8:9]
	v_add_u32_e32 v203, 0x6e80, v203
	global_load_dword v127, v203, s[8:9]
	s_mov_b64 exec, s[2:3]
	v_mov_b32_e32 v208, v10
	v_cmp_gt_u32_e32 vcc, 0x70000, v208
	s_mov_b64 s[40:41], vcc
	v_lshrrev_b32_e32 v209, 6, v208
	s_mov_b32 s1, 0x124924a
	v_mul_hi_u32 v210, v209, s1
	v_mul_u32_u24_e32 v209, 0xe0, v210
	v_lshrrev_b32_e32 v232, 6, v208
	v_sub_u32_e32 v209, v232, v209
	v_bfe_u32 v232, v208, 4, 2
	v_lshl_add_u32 v232, v210, 2, v232
	v_and_b32_e32 v210, 15, v208
	v_lshl_add_u32 v210, v209, 4, v210
	v_mov_b32_e32 v209, v232
	v_mul_u32_u24_e32 v211, 0x37400, v209
	v_lshl_add_u32 v211, v210, 2, v211
	v_add_u32_e32 v211, 0x3680, v211
	v_lshlrev_b32_e32 v212, 11, v210
	v_lshl_add_u32 v212, v209, 4, v212
	v_add_u32_e32 v212, 0xb00000, v212
	s_mov_b64 exec, s[40:41]
	global_load_dword v136, v211, s[8:9]
	v_add_u32_e32 v211, 0x6e80, v211
	global_load_dword v137, v211, s[8:9]
	v_add_u32_e32 v211, 0x6e80, v211
	global_load_dword v138, v211, s[8:9]
	v_add_u32_e32 v211, 0x6e80, v211
	global_load_dword v139, v211, s[8:9]
	v_add_u32_e32 v211, 0x6e80, v211
	global_load_dword v140, v211, s[8:9]
	v_add_u32_e32 v211, 0x6e80, v211
	global_load_dword v141, v211, s[8:9]
	v_add_u32_e32 v211, 0x6e80, v211
	global_load_dword v142, v211, s[8:9]
	v_add_u32_e32 v211, 0x6e80, v211
	global_load_dword v143, v211, s[8:9]
	s_mov_b64 exec, s[2:3]
	s_mul_i32 s0, s92, 1
	v_add_u32_e32 v216, s0, v10
	v_cmp_gt_u32_e32 vcc, 0x70000, v216
	s_mov_b64 s[42:43], vcc
	v_lshrrev_b32_e32 v217, 6, v216
	s_mov_b32 s1, 0x124924a
	v_mul_hi_u32 v218, v217, s1
	v_mul_u32_u24_e32 v217, 0xe0, v218
	v_lshrrev_b32_e32 v232, 6, v216
	v_sub_u32_e32 v217, v232, v217
	v_bfe_u32 v232, v216, 4, 2
	v_lshl_add_u32 v232, v218, 2, v232
	v_and_b32_e32 v218, 15, v216
	v_lshl_add_u32 v218, v217, 4, v218
	v_mov_b32_e32 v217, v232
	v_mul_u32_u24_e32 v219, 0x37400, v217
	v_lshl_add_u32 v219, v218, 2, v219
	v_add_u32_e32 v219, 0x3680, v219
	v_lshlrev_b32_e32 v220, 11, v218
	v_lshl_add_u32 v220, v217, 4, v220
	v_add_u32_e32 v220, 0xb00000, v220
	s_mov_b64 exec, s[42:43]
	global_load_dword v152, v219, s[8:9]
	v_add_u32_e32 v219, 0x6e80, v219
	global_load_dword v153, v219, s[8:9]
	v_add_u32_e32 v219, 0x6e80, v219
	global_load_dword v154, v219, s[8:9]
	v_add_u32_e32 v219, 0x6e80, v219
	global_load_dword v155, v219, s[8:9]
	v_add_u32_e32 v219, 0x6e80, v219
	global_load_dword v156, v219, s[8:9]
	v_add_u32_e32 v219, 0x6e80, v219
	global_load_dword v157, v219, s[8:9]
	v_add_u32_e32 v219, 0x6e80, v219
	global_load_dword v158, v219, s[8:9]
	v_add_u32_e32 v219, 0x6e80, v219
	global_load_dword v159, v219, s[8:9]
	s_mov_b64 exec, s[2:3]
	v_mov_b32_e32 v224, v10
	v_cmp_gt_u32_e32 vcc, 0x6000, v224
	s_mov_b64 s[44:45], vcc
	v_lshrrev_b32_e32 v225, 6, v224
	s_mov_b32 s1, 0x5555556
	v_mul_hi_u32 v226, v225, s1
	v_mul_u32_u24_e32 v225, 0x30, v226
	v_lshrrev_b32_e32 v232, 6, v224
	v_sub_u32_e32 v225, v232, v225
	v_bfe_u32 v232, v224, 4, 2
	v_lshl_add_u32 v232, v226, 2, v232
	v_and_b32_e32 v226, 15, v224
	v_lshl_add_u32 v226, v225, 4, v226
	v_mov_b32_e32 v225, v232
	v_mul_u32_u24_e32 v227, 0x6000, v225
	v_lshl_add_u32 v227, v226, 2, v227
	v_lshlrev_b32_e32 v228, 9, v226
	v_lshl_add_u32 v228, v225, 4, v228
	v_add_u32_e32 v228, 0x1200000, v228
	v_lshlrev_b32_e32 v229, 5, v225
	s_mov_b64 exec, s[44:45]
	global_load_dword v176, v227, s[10:11]
	v_add_u32_e32 v227, 0xc00, v227
	global_load_dword v177, v227, s[10:11]
	v_add_u32_e32 v227, 0xc00, v227
	global_load_dword v178, v227, s[10:11]
	v_add_u32_e32 v227, 0xc00, v227
	global_load_dword v179, v227, s[10:11]
	v_add_u32_e32 v227, 0xc00, v227
	global_load_dword v180, v227, s[10:11]
	v_add_u32_e32 v227, 0xc00, v227
	global_load_dword v181, v227, s[10:11]
	v_add_u32_e32 v227, 0xc00, v227
	global_load_dword v182, v227, s[10:11]
	v_add_u32_e32 v227, 0xc00, v227
	global_load_dword v183, v227, s[10:11]
	global_load_dwordx4 v[184:187], v229, s[12:13]
	global_load_dwordx4 v[188:191], v229, s[12:13] offset:16
	s_mov_b64 exec, s[2:3]
	s_waitcnt vmcnt(0)
	s_mov_b64 exec, s[36:37]
	v_cvt_pk_bf16_f32 v104, v104, v105
	v_cvt_pk_bf16_f32 v105, v106, v107
	v_cvt_pk_bf16_f32 v106, v108, v109
	v_cvt_pk_bf16_f32 v107, v110, v111
	global_store_dwordx4 v196, v[104:107], s[94:95]
	s_mov_b64 exec, s[2:3]
	s_mov_b64 exec, s[38:39]
	v_cvt_pk_bf16_f32 v120, v120, v121
	v_cvt_pk_bf16_f32 v121, v122, v123
	v_cvt_pk_bf16_f32 v122, v124, v125
	v_cvt_pk_bf16_f32 v123, v126, v127
	global_store_dwordx4 v204, v[120:123], s[94:95]
	s_mov_b64 exec, s[2:3]
	s_mov_b64 exec, s[40:41]
	v_cvt_pk_bf16_f32 v136, v136, v137
	v_cvt_pk_bf16_f32 v137, v138, v139
	v_cvt_pk_bf16_f32 v138, v140, v141
	v_cvt_pk_bf16_f32 v139, v142, v143
	global_store_dwordx4 v212, v[136:139], s[94:95]
	s_mov_b64 exec, s[2:3]
	s_mov_b64 exec, s[42:43]
	v_cvt_pk_bf16_f32 v152, v152, v153
	v_cvt_pk_bf16_f32 v153, v154, v155
	v_cvt_pk_bf16_f32 v154, v156, v157
	v_cvt_pk_bf16_f32 v155, v158, v159
	global_store_dwordx4 v220, v[152:155], s[94:95]
	s_mov_b64 exec, s[2:3]
	s_mov_b64 exec, s[44:45]
	v_mul_f32_e32 v176, v176, v184
	v_mul_f32_e32 v177, v177, v185
	v_mul_f32_e32 v178, v178, v186
	v_mul_f32_e32 v179, v179, v187
	v_mul_f32_e32 v180, v180, v188
	v_mul_f32_e32 v181, v181, v189
	v_mul_f32_e32 v182, v182, v190
	v_mul_f32_e32 v183, v183, v191
	v_cvt_pk_bf16_f32 v176, v176, v177
	v_cvt_pk_bf16_f32 v177, v178, v179
	v_cvt_pk_bf16_f32 v178, v180, v181
	v_cvt_pk_bf16_f32 v179, v182, v183
	global_store_dwordx4 v228, v[176:179], s[94:95]
	s_mov_b64 exec, s[2:3]
	s_mul_i32 s0, s92, 2
	v_add_u32_e32 v192, s0, v10
	v_cmp_gt_u32_e32 vcc, 0x6d000, v192
	s_mov_b64 s[36:37], vcc
	v_lshrrev_b32_e32 v193, 6, v192
	s_mov_b32 s1, 0x12c9fb5
	v_mul_hi_u32 v194, v193, s1
	v_mul_u32_u24_e32 v193, 0xda, v194
	v_lshrrev_b32_e32 v232, 6, v192
	v_sub_u32_e32 v193, v232, v193
	v_bfe_u32 v232, v192, 4, 2
	v_lshl_add_u32 v232, v194, 2, v232
	v_and_b32_e32 v194, 15, v192
	v_lshl_add_u32 v194, v193, 4, v194
	v_mov_b32_e32 v193, v232
	v_mul_u32_u24_e32 v195, 0x37400, v193
	v_lshl_add_u32 v195, v194, 2, v195
	v_lshlrev_b32_e32 v196, 11, v194
	v_lshl_add_u32 v196, v193, 4, v196
	v_add_u32_e32 v196, 0x400000, v196
	s_mov_b64 exec, s[36:37]
	global_load_dword v104, v195, s[8:9]
	v_add_u32_e32 v195, 0x6e80, v195
	global_load_dword v105, v195, s[8:9]
	v_add_u32_e32 v195, 0x6e80, v195
	global_load_dword v106, v195, s[8:9]
	v_add_u32_e32 v195, 0x6e80, v195
	global_load_dword v107, v195, s[8:9]
	v_add_u32_e32 v195, 0x6e80, v195
	global_load_dword v108, v195, s[8:9]
	v_add_u32_e32 v195, 0x6e80, v195
	global_load_dword v109, v195, s[8:9]
	v_add_u32_e32 v195, 0x6e80, v195
	global_load_dword v110, v195, s[8:9]
	v_add_u32_e32 v195, 0x6e80, v195
	global_load_dword v111, v195, s[8:9]
	s_mov_b64 exec, s[2:3]
	s_mul_i32 s0, s92, 3
	v_add_u32_e32 v200, s0, v10
	v_cmp_gt_u32_e32 vcc, 0x6d000, v200
	s_mov_b64 s[38:39], vcc
	v_lshrrev_b32_e32 v201, 6, v200
	s_mov_b32 s1, 0x12c9fb5
	v_mul_hi_u32 v202, v201, s1
	v_mul_u32_u24_e32 v201, 0xda, v202
	v_lshrrev_b32_e32 v232, 6, v200
	v_sub_u32_e32 v201, v232, v201
	v_bfe_u32 v232, v200, 4, 2
	v_lshl_add_u32 v232, v202, 2, v232
	v_and_b32_e32 v202, 15, v200
	v_lshl_add_u32 v202, v201, 4, v202
	v_mov_b32_e32 v201, v232
	v_mul_u32_u24_e32 v203, 0x37400, v201
	v_lshl_add_u32 v203, v202, 2, v203
	v_lshlrev_b32_e32 v204, 11, v202
	v_lshl_add_u32 v204, v201, 4, v204
	v_add_u32_e32 v204, 0x400000, v204
	s_mov_b64 exec, s[38:39]
	global_load_dword v120, v203, s[8:9]
	v_add_u32_e32 v203, 0x6e80, v203
	global_load_dword v121, v203, s[8:9]
	v_add_u32_e32 v203, 0x6e80, v203
	global_load_dword v122, v203, s[8:9]
	v_add_u32_e32 v203, 0x6e80, v203
	global_load_dword v123, v203, s[8:9]
	v_add_u32_e32 v203, 0x6e80, v203
	global_load_dword v124, v203, s[8:9]
	v_add_u32_e32 v203, 0x6e80, v203
	global_load_dword v125, v203, s[8:9]
	v_add_u32_e32 v203, 0x6e80, v203
	global_load_dword v126, v203, s[8:9]
	v_add_u32_e32 v203, 0x6e80, v203
	global_load_dword v127, v203, s[8:9]
	s_mov_b64 exec, s[2:3]
	s_mul_i32 s0, s92, 2
	v_add_u32_e32 v208, s0, v10
	v_cmp_gt_u32_e32 vcc, 0x70000, v208
	s_mov_b64 s[40:41], vcc
	v_lshrrev_b32_e32 v209, 6, v208
	s_mov_b32 s1, 0x124924a
	v_mul_hi_u32 v210, v209, s1
	v_mul_u32_u24_e32 v209, 0xe0, v210
	v_lshrrev_b32_e32 v232, 6, v208
	v_sub_u32_e32 v209, v232, v209
	v_bfe_u32 v232, v208, 4, 2
	v_lshl_add_u32 v232, v210, 2, v232
	v_and_b32_e32 v210, 15, v208
	v_lshl_add_u32 v210, v209, 4, v210
	v_mov_b32_e32 v209, v232
	v_mul_u32_u24_e32 v211, 0x37400, v209
	v_lshl_add_u32 v211, v210, 2, v211
	v_add_u32_e32 v211, 0x3680, v211
	v_lshlrev_b32_e32 v212, 11, v210
	v_lshl_add_u32 v212, v209, 4, v212
	v_add_u32_e32 v212, 0xb00000, v212
	s_mov_b64 exec, s[40:41]
	global_load_dword v136, v211, s[8:9]
	v_add_u32_e32 v211, 0x6e80, v211
	global_load_dword v137, v211, s[8:9]
	v_add_u32_e32 v211, 0x6e80, v211
	global_load_dword v138, v211, s[8:9]
	v_add_u32_e32 v211, 0x6e80, v211
	global_load_dword v139, v211, s[8:9]
	v_add_u32_e32 v211, 0x6e80, v211
	global_load_dword v140, v211, s[8:9]
	v_add_u32_e32 v211, 0x6e80, v211
	global_load_dword v141, v211, s[8:9]
	v_add_u32_e32 v211, 0x6e80, v211
	global_load_dword v142, v211, s[8:9]
	v_add_u32_e32 v211, 0x6e80, v211
	global_load_dword v143, v211, s[8:9]
	s_mov_b64 exec, s[2:3]
	s_mul_i32 s0, s92, 3
	v_add_u32_e32 v216, s0, v10
	v_cmp_gt_u32_e32 vcc, 0x70000, v216
	s_mov_b64 s[42:43], vcc
	v_lshrrev_b32_e32 v217, 6, v216
	s_mov_b32 s1, 0x124924a
	v_mul_hi_u32 v218, v217, s1
	v_mul_u32_u24_e32 v217, 0xe0, v218
	v_lshrrev_b32_e32 v232, 6, v216
	v_sub_u32_e32 v217, v232, v217
	v_bfe_u32 v232, v216, 4, 2
	v_lshl_add_u32 v232, v218, 2, v232
	v_and_b32_e32 v218, 15, v216
	v_lshl_add_u32 v218, v217, 4, v218
	v_mov_b32_e32 v217, v232
	v_mul_u32_u24_e32 v219, 0x37400, v217
	v_lshl_add_u32 v219, v218, 2, v219
	v_add_u32_e32 v219, 0x3680, v219
	v_lshlrev_b32_e32 v220, 11, v218
	v_lshl_add_u32 v220, v217, 4, v220
	v_add_u32_e32 v220, 0xb00000, v220
	s_mov_b64 exec, s[42:43]
	global_load_dword v152, v219, s[8:9]
	v_add_u32_e32 v219, 0x6e80, v219
	global_load_dword v153, v219, s[8:9]
	v_add_u32_e32 v219, 0x6e80, v219
	global_load_dword v154, v219, s[8:9]
	v_add_u32_e32 v219, 0x6e80, v219
	global_load_dword v155, v219, s[8:9]
	v_add_u32_e32 v219, 0x6e80, v219
	global_load_dword v156, v219, s[8:9]
	v_add_u32_e32 v219, 0x6e80, v219
	global_load_dword v157, v219, s[8:9]
	v_add_u32_e32 v219, 0x6e80, v219
	global_load_dword v158, v219, s[8:9]
	v_add_u32_e32 v219, 0x6e80, v219
	global_load_dword v159, v219, s[8:9]
	s_mov_b64 exec, s[2:3]
	v_mov_b32_e32 v224, v10
	v_cmp_gt_u32_e32 vcc, 0x4000, v224
	s_mov_b64 s[44:45], vcc
	v_lshrrev_b32_e32 v225, 6, v224
	v_lshrrev_b32_e32 v226, 12, v224
	v_lshlrev_b32_e32 v225, 6, v226
	v_lshrrev_b32_e32 v232, 6, v224
	v_sub_u32_e32 v225, v232, v225
	v_bfe_u32 v232, v224, 4, 2
	v_lshl_add_u32 v232, v226, 2, v232
	v_and_b32_e32 v226, 15, v224
	v_lshl_add_u32 v226, v225, 4, v226
	v_mov_b32_e32 v225, v232
	v_mul_u32_u24_e32 v227, 0x8000, v225
	v_lshl_add_u32 v227, v226, 2, v227
	v_lshlrev_b32_e32 v228, 8, v226
	v_lshl_add_u32 v228, v225, 4, v228
	v_add_u32_e32 v228, 0x1280000, v228
	v_lshlrev_b32_e32 v229, 5, v225
	s_mov_b64 exec, s[44:45]
	global_load_dword v176, v227, s[14:15]
	v_add_u32_e32 v227, 0x1000, v227
	global_load_dword v177, v227, s[14:15]
	v_add_u32_e32 v227, 0x1000, v227
	global_load_dword v178, v227, s[14:15]
	v_add_u32_e32 v227, 0x1000, v227
	global_load_dword v179, v227, s[14:15]
	v_add_u32_e32 v227, 0x1000, v227
	global_load_dword v180, v227, s[14:15]
	v_add_u32_e32 v227, 0x1000, v227
	global_load_dword v181, v227, s[14:15]
	v_add_u32_e32 v227, 0x1000, v227
	global_load_dword v182, v227, s[14:15]
	v_add_u32_e32 v227, 0x1000, v227
	global_load_dword v183, v227, s[14:15]
	global_load_dwordx4 v[184:187], v229, s[16:17]
	global_load_dwordx4 v[188:191], v229, s[16:17] offset:16
	s_mov_b64 exec, s[2:3]
	s_waitcnt vmcnt(0)
	s_mov_b64 exec, s[36:37]
	v_cvt_pk_bf16_f32 v104, v104, v105
	v_cvt_pk_bf16_f32 v105, v106, v107
	v_cvt_pk_bf16_f32 v106, v108, v109
	v_cvt_pk_bf16_f32 v107, v110, v111
	global_store_dwordx4 v196, v[104:107], s[94:95]
	s_mov_b64 exec, s[2:3]
	s_mov_b64 exec, s[38:39]
	v_cvt_pk_bf16_f32 v120, v120, v121
	v_cvt_pk_bf16_f32 v121, v122, v123
	v_cvt_pk_bf16_f32 v122, v124, v125
	v_cvt_pk_bf16_f32 v123, v126, v127
	global_store_dwordx4 v204, v[120:123], s[94:95]
	s_mov_b64 exec, s[2:3]
	s_mov_b64 exec, s[40:41]
	v_cvt_pk_bf16_f32 v136, v136, v137
	v_cvt_pk_bf16_f32 v137, v138, v139
	v_cvt_pk_bf16_f32 v138, v140, v141
	v_cvt_pk_bf16_f32 v139, v142, v143
	global_store_dwordx4 v212, v[136:139], s[94:95]
	s_mov_b64 exec, s[2:3]
	s_mov_b64 exec, s[42:43]
	v_cvt_pk_bf16_f32 v152, v152, v153
	v_cvt_pk_bf16_f32 v153, v154, v155
	v_cvt_pk_bf16_f32 v154, v156, v157
	v_cvt_pk_bf16_f32 v155, v158, v159
	global_store_dwordx4 v220, v[152:155], s[94:95]
	s_mov_b64 exec, s[2:3]
	s_mov_b64 exec, s[44:45]
	v_mul_f32_e32 v176, v176, v184
	v_mul_f32_e32 v177, v177, v185
	v_mul_f32_e32 v178, v178, v186
	v_mul_f32_e32 v179, v179, v187
	v_mul_f32_e32 v180, v180, v188
	v_mul_f32_e32 v181, v181, v189
	v_mul_f32_e32 v182, v182, v190
	v_mul_f32_e32 v183, v183, v191
	v_cvt_pk_bf16_f32 v176, v176, v177
	v_cvt_pk_bf16_f32 v177, v178, v179
	v_cvt_pk_bf16_f32 v178, v180, v181
	v_cvt_pk_bf16_f32 v179, v182, v183
	global_store_dwordx4 v228, v[176:179], s[94:95]
	s_mov_b64 exec, s[2:3]
	v_cmp_gt_u32_e32 vcc, 0x3000, v10
	v_lshlrev_b32_e32 v192, 4, v10
	v_add_u32_e32 v192, 0xad0000, v192
	v_mov_b32_e32 v104, 0
	v_mov_b32_e32 v105, 0
	v_mov_b32_e32 v106, 0
	v_mov_b32_e32 v107, 0
	s_and_b64 exec, s[2:3], vcc
	global_store_dwordx4 v192, v[104:107], s[94:95]
	s_mov_b64 exec, s[2:3]
	.p2align 6
	s_nop 0
	s_nop 0

.LBB0_228:
	s_lshr_b32 s0, s71, 3
	s_cmp_lt_u32 s0, 56
	s_cbranch_scc1 .Lp1conv_skip
	v_readlane_b32 s20, v253, 48
	v_readlane_b32 s0, v253, 2
	v_readlane_b32 s1, v253, 3
	v_readlane_b32 s2, v254, 1
	v_readlane_b32 s3, v254, 2
	v_readlane_b32 s4, v253, 36
	v_readlane_b32 s5, v253, 37
	v_readlane_b32 s6, v253, 38
	v_readlane_b32 s7, v253, 39
	v_readlane_b32 s8, v253, 40
	v_readlane_b32 s9, v253, 41
	v_readlane_b32 s22, v253, 42
	v_readlane_b32 s23, v253, 43
	s_sub_i32 s20, s20, 0x7000
	v_add_u32_e32 v29, s20, v170
	s_lshl_b32 s21, s45, 20
	s_add_u32 s2, s2, s21
	s_addc_u32 s3, s3, 0
	s_lshl_b32 s21, s45, 21
	s_add_u32 s4, s4, s21
	s_addc_u32 s5, s5, 0
	s_add_u32 s6, s6, s21
	s_addc_u32 s7, s7, 0
	s_add_u32 s8, s8, s21
	s_addc_u32 s9, s9, 0
	s_lshl_b32 s21, s45, 22
	s_add_u32 s22, s22, s21
	s_addc_u32 s23, s23, 0
	s_mov_b64 s[20:21], exec
	v_mov_b32_e32 v40, v29
	v_cmp_gt_u32_e32 vcc, 0x20000, v40
	s_mov_b64 s[10:11], vcc
	v_lshrrev_b32_e32 v41, 6, v40
	v_lshrrev_b32_e32 v42, 12, v40
	v_lshlrev_b32_e32 v41, 6, v42
	v_lshrrev_b32_e32 v44, 6, v40
	v_sub_u32_e32 v41, v44, v41
	v_bfe_u32 v44, v40, 4, 2
	v_lshl_add_u32 v44, v42, 2, v44
	v_and_b32_e32 v42, 15, v40
	v_lshl_add_u32 v42, v41, 4, v42
	v_mov_b32_e32 v41, v44
	v_mul_u32_u24_e32 v43, 0x8000, v41
	v_lshl_add_u32 v43, v42, 2, v43
	v_lshlrev_b32_e32 v24, 11, v42
	v_lshl_add_u32 v24, v41, 4, v24
	v_add_u32_e32 v24, 0x1700000, v24
	s_mov_b64 exec, s[10:11]
	global_load_dword v0, v43, s[22:23]
	v_add_u32_e32 v43, 0x1000, v43
	global_load_dword v1, v43, s[22:23]
	v_add_u32_e32 v43, 0x1000, v43
	global_load_dword v2, v43, s[22:23]
	v_add_u32_e32 v43, 0x1000, v43
	global_load_dword v3, v43, s[22:23]
	v_add_u32_e32 v43, 0x1000, v43
	global_load_dword v4, v43, s[22:23]
	v_add_u32_e32 v43, 0x1000, v43
	global_load_dword v5, v43, s[22:23]
	v_add_u32_e32 v43, 0x1000, v43
	global_load_dword v6, v43, s[22:23]
	v_add_u32_e32 v43, 0x1000, v43
	global_load_dword v7, v43, s[22:23]
	s_mov_b64 exec, s[20:21]
	s_mov_b32 s30, 0x19000
	v_add_u32_e32 v40, s30, v29
	v_cmp_gt_u32_e32 vcc, 0x20000, v40
	s_mov_b64 s[12:13], vcc
	v_lshrrev_b32_e32 v41, 6, v40
	v_lshrrev_b32_e32 v42, 12, v40
	v_lshlrev_b32_e32 v41, 6, v42
	v_lshrrev_b32_e32 v44, 6, v40
	v_sub_u32_e32 v41, v44, v41
	v_bfe_u32 v44, v40, 4, 2
	v_lshl_add_u32 v44, v42, 2, v44
	v_and_b32_e32 v42, 15, v40
	v_lshl_add_u32 v42, v41, 4, v42
	v_mov_b32_e32 v41, v44
	v_mul_u32_u24_e32 v43, 0x8000, v41
	v_lshl_add_u32 v43, v42, 2, v43
	v_lshlrev_b32_e32 v25, 11, v42
	v_lshl_add_u32 v25, v41, 4, v25
	v_add_u32_e32 v25, 0x1700000, v25
	s_mov_b64 exec, s[12:13]
	global_load_dword v8, v43, s[22:23]
	v_add_u32_e32 v43, 0x1000, v43
	global_load_dword v9, v43, s[22:23]
	v_add_u32_e32 v43, 0x1000, v43
	global_load_dword v10, v43, s[22:23]
	v_add_u32_e32 v43, 0x1000, v43
	global_load_dword v11, v43, s[22:23]
	v_add_u32_e32 v43, 0x1000, v43
	global_load_dword v12, v43, s[22:23]
	v_add_u32_e32 v43, 0x1000, v43
	global_load_dword v13, v43, s[22:23]
	v_add_u32_e32 v43, 0x1000, v43
	global_load_dword v14, v43, s[22:23]
	v_add_u32_e32 v43, 0x1000, v43
	global_load_dword v15, v43, s[22:23]
	s_mov_b64 exec, s[20:21]
	v_mov_b32_e32 v40, v29
	v_cmp_gt_u32_e32 vcc, 0x10000, v40
	s_mov_b64 s[14:15], vcc
	v_lshrrev_b32_e32 v41, 6, v40
	v_lshrrev_b32_e32 v42, 12, v40
	v_lshlrev_b32_e32 v41, 6, v42
	v_lshrrev_b32_e32 v44, 6, v40
	v_sub_u32_e32 v41, v44, v41
	v_bfe_u32 v44, v40, 4, 2
	v_lshl_add_u32 v44, v42, 2, v44
	v_and_b32_e32 v42, 15, v40
	v_lshl_add_u32 v42, v41, 4, v42
	v_mov_b32_e32 v41, v44
	v_mul_u32_u24_e32 v43, 0x8000, v41
	v_lshl_add_u32 v43, v42, 2, v43
	v_lshlrev_b32_e32 v26, 10, v42
	v_lshl_add_u32 v26, v41, 4, v26
	v_add_u32_e32 v26, 0x1400000, v26
	s_mov_b64 exec, s[14:15]
	global_load_dword v16, v43, s[4:5]
	v_add_u32_e32 v43, 0x1000, v43
	global_load_dword v17, v43, s[4:5]
	v_add_u32_e32 v43, 0x1000, v43
	global_load_dword v18, v43, s[4:5]
	v_add_u32_e32 v43, 0x1000, v43
	global_load_dword v19, v43, s[4:5]
	v_add_u32_e32 v43, 0x1000, v43
	global_load_dword v20, v43, s[4:5]
	v_add_u32_e32 v43, 0x1000, v43
	global_load_dword v21, v43, s[4:5]
	v_add_u32_e32 v43, 0x1000, v43
	global_load_dword v22, v43, s[4:5]
	v_add_u32_e32 v43, 0x1000, v43
	global_load_dword v23, v43, s[4:5]
	s_mov_b64 exec, s[20:21]
	v_mov_b32_e32 v40, v29
	v_cmp_gt_u32_e32 vcc, 0x10000, v40
	s_mov_b64 s[16:17], vcc
	v_lshrrev_b32_e32 v41, 6, v40
	v_lshrrev_b32_e32 v42, 12, v40
	v_lshlrev_b32_e32 v41, 6, v42
	v_lshrrev_b32_e32 v44, 6, v40
	v_sub_u32_e32 v41, v44, v41
	v_bfe_u32 v44, v40, 4, 2
	v_lshl_add_u32 v44, v42, 2, v44
	v_and_b32_e32 v42, 15, v40
	v_lshl_add_u32 v42, v41, 4, v42
	v_mov_b32_e32 v41, v44
	v_mul_u32_u24_e32 v43, 0x8000, v41
	v_lshl_add_u32 v43, v42, 2, v43
	v_lshlrev_b32_e32 v27, 10, v42
	v_lshl_add_u32 v27, v41, 4, v27
	v_add_u32_e32 v27, 0x1500000, v27
	s_mov_b64 exec, s[16:17]
	global_load_dword v32, v43, s[6:7]
	v_add_u32_e32 v43, 0x1000, v43
	global_load_dword v33, v43, s[6:7]
	v_add_u32_e32 v43, 0x1000, v43
	global_load_dword v34, v43, s[6:7]
	v_add_u32_e32 v43, 0x1000, v43
	global_load_dword v35, v43, s[6:7]
	v_add_u32_e32 v43, 0x1000, v43
	global_load_dword v36, v43, s[6:7]
	v_add_u32_e32 v43, 0x1000, v43
	global_load_dword v37, v43, s[6:7]
	v_add_u32_e32 v43, 0x1000, v43
	global_load_dword v38, v43, s[6:7]
	v_add_u32_e32 v43, 0x1000, v43
	global_load_dword v39, v43, s[6:7]
	s_mov_b64 exec, s[20:21]
	v_mov_b32_e32 v40, v29
	v_cmp_gt_u32_e32 vcc, 0x10000, v40
	s_mov_b64 s[18:19], vcc
	v_lshrrev_b32_e32 v41, 6, v40
	v_lshrrev_b32_e32 v42, 12, v40
	v_lshlrev_b32_e32 v41, 6, v42
	v_lshrrev_b32_e32 v44, 6, v40
	v_sub_u32_e32 v41, v44, v41
	v_bfe_u32 v44, v40, 4, 2
	v_lshl_add_u32 v44, v42, 2, v44
	v_and_b32_e32 v42, 15, v40
	v_lshl_add_u32 v42, v41, 4, v42
	v_mov_b32_e32 v41, v44
	v_mul_u32_u24_e32 v43, 0x8000, v41
	v_lshl_add_u32 v43, v42, 2, v43
	v_lshlrev_b32_e32 v28, 10, v42
	v_lshl_add_u32 v28, v41, 4, v28
	v_add_u32_e32 v28, 0x1600000, v28
	s_mov_b64 exec, s[18:19]
	global_load_dword v48, v43, s[8:9]
	v_add_u32_e32 v43, 0x1000, v43
	global_load_dword v49, v43, s[8:9]
	v_add_u32_e32 v43, 0x1000, v43
	global_load_dword v50, v43, s[8:9]
	v_add_u32_e32 v43, 0x1000, v43
	global_load_dword v51, v43, s[8:9]
	v_add_u32_e32 v43, 0x1000, v43
	global_load_dword v52, v43, s[8:9]
	v_add_u32_e32 v43, 0x1000, v43
	global_load_dword v53, v43, s[8:9]
	v_add_u32_e32 v43, 0x1000, v43
	global_load_dword v54, v43, s[8:9]
	v_add_u32_e32 v43, 0x1000, v43
	global_load_dword v55, v43, s[8:9]
	s_mov_b64 exec, s[20:21]
	s_waitcnt vmcnt(0)
	s_mov_b64 exec, s[10:11]
	v_cvt_pk_bf16_f32 v0, v0, v1
	v_cvt_pk_bf16_f32 v1, v2, v3
	v_cvt_pk_bf16_f32 v2, v4, v5
	v_cvt_pk_bf16_f32 v3, v6, v7
	global_store_dwordx4 v24, v[0:3], s[0:1]
	s_mov_b64 exec, s[20:21]
	s_mov_b64 exec, s[12:13]
	v_cvt_pk_bf16_f32 v8, v8, v9
	v_cvt_pk_bf16_f32 v9, v10, v11
	v_cvt_pk_bf16_f32 v10, v12, v13
	v_cvt_pk_bf16_f32 v11, v14, v15
	global_store_dwordx4 v25, v[8:11], s[0:1]
	s_mov_b64 exec, s[20:21]
	s_mov_b64 exec, s[14:15]
	v_cvt_pk_bf16_f32 v16, v16, v17
	v_cvt_pk_bf16_f32 v17, v18, v19
	v_cvt_pk_bf16_f32 v18, v20, v21
	v_cvt_pk_bf16_f32 v19, v22, v23
	global_store_dwordx4 v26, v[16:19], s[0:1]
	s_mov_b64 exec, s[20:21]
	s_mov_b64 exec, s[16:17]
	v_cvt_pk_bf16_f32 v32, v32, v33
	v_cvt_pk_bf16_f32 v33, v34, v35
	v_cvt_pk_bf16_f32 v34, v36, v37
	v_cvt_pk_bf16_f32 v35, v38, v39
	global_store_dwordx4 v27, v[32:35], s[0:1]
	s_mov_b64 exec, s[20:21]
	s_mov_b64 exec, s[18:19]
	v_cvt_pk_bf16_f32 v48, v48, v49
	v_cvt_pk_bf16_f32 v49, v50, v51
	v_cvt_pk_bf16_f32 v50, v52, v53
	v_cvt_pk_bf16_f32 v51, v54, v55
	global_store_dwordx4 v28, v[48:51], s[0:1]
	s_mov_b64 exec, s[20:21]
	v_mov_b32_e32 v40, v29
	v_cmp_gt_u32_e32 vcc, 0x8000, v40
	s_mov_b64 s[10:11], vcc
	v_lshrrev_b32_e32 v41, 6, v40
	v_lshrrev_b32_e32 v42, 11, v40
	v_lshlrev_b32_e32 v41, 5, v42
	v_lshrrev_b32_e32 v44, 6, v40
	v_sub_u32_e32 v41, v44, v41
	v_bfe_u32 v44, v40, 4, 2
	v_lshl_add_u32 v44, v42, 2, v44
	v_and_b32_e32 v42, 15, v40
	v_lshl_add_u32 v42, v41, 4, v42
	v_mov_b32_e32 v41, v44
	v_mul_u32_u24_e32 v43, 0x4000, v41
	v_lshl_add_u32 v43, v42, 2, v43
	v_lshlrev_b32_e32 v24, 10, v42
	v_lshl_add_u32 v24, v41, 4, v24
	v_add_u32_e32 v24, 0x1300000, v24
	s_mov_b64 exec, s[10:11]
	global_load_dword v0, v43, s[2:3]
	v_add_u32_e32 v43, 0x800, v43
	global_load_dword v1, v43, s[2:3]
	v_add_u32_e32 v43, 0x800, v43
	global_load_dword v2, v43, s[2:3]
	v_add_u32_e32 v43, 0x800, v43
	global_load_dword v3, v43, s[2:3]
	v_add_u32_e32 v43, 0x800, v43
	global_load_dword v4, v43, s[2:3]
	v_add_u32_e32 v43, 0x800, v43
	global_load_dword v5, v43, s[2:3]
	v_add_u32_e32 v43, 0x800, v43
	global_load_dword v6, v43, s[2:3]
	v_add_u32_e32 v43, 0x800, v43
	global_load_dword v7, v43, s[2:3]
	s_mov_b64 exec, s[20:21]
	s_waitcnt vmcnt(0)
	s_mov_b64 exec, s[10:11]
	v_cvt_pk_bf16_f32 v0, v0, v1
	v_cvt_pk_bf16_f32 v1, v2, v3
	v_cvt_pk_bf16_f32 v2, v4, v5
	v_cvt_pk_bf16_f32 v3, v6, v7
	global_store_dwordx4 v24, v[0:3], s[0:1]
	s_mov_b64 exec, s[20:21]
	s_nop 0
	s_nop 0
	s_nop 0
	s_nop 0
	s_nop 0
	s_nop 0
	s_nop 0
	s_nop 0
	s_nop 0
	s_nop 0
